# K-loop heads of both GEMM loops aligned to 64 B (p2align 6) on top of v41
# baseline (speedup 1.0000x reference)
; #define PG8_STAGE(bufoff, gbase, voff) do { _Pragma("unroll") for (int _i = 0; _i < 2; ++_i) \
;         __builtin_amdgcn_global_load_lds((const unsigned*)((const char*)(gbase) + (voff)[_i]), (LAS unsigned*)(lds + (bufoff) + ldsw + _i * 8192), 16, 0, 0); } while (0)
; #define PG8_LDA(dst, b, h) do { _Pragma("unroll") for (int m = 0; m < 4; ++m) _Pragma("unroll") for (int k = 0; k < 2; ++k) dst[m][k] = *(const LAS bf16x8*)(lds + PG8_SA(b, h) + aoff + m * 2048 + k * 1024); } while (0)
; #define PG8_LDB(dst, b, h) do { _Pragma("unroll") for (int n = 0; n < 2; ++n) _Pragma("unroll") for (int k = 0; k < 2; ++k) dst[n][k] = *(const LAS bf16x8*)(lds + PG8_SB(b, h) + boff + n * 2048 + k * 1024); } while (0)
; #define PG8_MMA(ai, bj, At, Bt) do { __builtin_amdgcn_s_setprio(1); _Pragma("unroll") for (int m = 0; m < 4; ++m) _Pragma("unroll") for (int n = 0; n < 2; ++n) _Pragma("unroll") for (int k = 0; k < 2; ++k) \
;         acc[ai][bj][m][n] = __builtin_amdgcn_mfma_f32_16x16x32_bf16(Bt[n][k], At[m][k], acc[ai][bj][m][n], 0, 0, 0); __builtin_amdgcn_s_setprio(0); } while (0)
; #define PG8_WAIT_V(n) asm volatile("s_waitcnt vmcnt(" #n ")" ::: "memory")
; #define PG8_WAIT_L(n) asm volatile("s_waitcnt lgkmcnt(" #n ")" ::: "memory")
; #define PG8_BAR __builtin_amdgcn_s_barrier()
; #define PG8_SCHED __builtin_amdgcn_sched_barrier(0)
; template <class Epi>
; __device__ __forceinline__ void gemm_phase(LAS unsigned char* lds, const Gemm g, const StaticOrder& S, const Epi& E) {
;     ...
;         for (int t = 0; t < nt; t += 2) {
;             const bool last = (t == nt - 2);
;             const char* a1 = cA + (size_t)(t + 1) * kstep;
;             const char* a2 = last ? nA : cA + (size_t)(t + 2) * kstep; const char* b2 = last ? nB : cB + (size_t)(t + 2) * kstep;
;             const char* a3 = a2 + kstep; const char* b3 = b2 + kstep;
;             PG8_LDB(B0, 0, 0); PG8_LDB(B1, 0, 1); PG8_SCHED; PG8_LDA(At, 0, 0); PG8_STAGE(PG8_SA(1, 1), a1 + hA, voffA);
;             PG8_WAIT_V(8); PG8_WAIT_L(0); PG8_BAR; PG8_MMA(0, 0, At, B0); PG8_MMA(0, 1, At, B1); PG8_BAR; PG8_SCHED;
;             PG8_LDA(At, 0, 1); PG8_STAGE(PG8_SB(0, 0), b2, voffB); PG8_STAGE(PG8_SB(0, 1), b2 + hB, voffB); PG8_STAGE(PG8_SA(0, 0), a2, voffA);
;             PG8_WAIT_V(8); PG8_WAIT_L(0); PG8_BAR; PG8_MMA(1, 0, At, B0); PG8_MMA(1, 1, At, B1); PG8_BAR; PG8_SCHED;
.Lpeel_342:
	s_add_i32 m0, s42, 0xc000
	ds_read_b128 v[128:131], v240
	ds_read_b128 v[132:135], v240 offset:1024
	ds_read_b128 v[136:139], v240 offset:2048
	ds_read_b128 v[140:143], v240 offset:3072
	ds_read_b128 v[144:147], v240 offset:16384
	ds_read_b128 v[148:151], v240 offset:17408
	ds_read_b128 v[152:155], v240 offset:18432
	ds_read_b128 v[156:159], v240 offset:19456
	ds_read_b128 v[160:163], v191
	ds_read_b128 v[180:183], v191 offset:1024
	ds_read_b128 v[184:187], v191 offset:2048
	ds_read_b128 v[192:195], v191 offset:3072
	ds_read_b128 v[206:209], v191 offset:4096
	ds_read_b128 v[210:213], v191 offset:5120
	ds_read_b128 v[214:217], v191 offset:6144
	ds_read_b128 v[218:221], v191 offset:7168
	global_load_lds_dwordx4 v176, s[4:5]
	s_add_i32 m0, s42, 0xe000
	s_nop 0
	global_load_lds_dwordx4 v178, s[4:5]
	s_add_i32 s56, s34, 2
	s_add_u32 s57, s4, 0x80
	s_addc_u32 s35, s5, 0
	s_add_i32 s60, 0, 0x10000
	s_cmp_eq_u32 s50, s34
	s_cselect_b32 s35, s29, s35
	s_cselect_b32 s34, s28, s57
	s_cselect_b32 s59, s31, s37
	s_cselect_b32 s58, s30, s36
	s_add_i32 s57, 0, 0x14000
	s_waitcnt vmcnt(8)
	s_waitcnt lgkmcnt(0)
	s_barrier
	s_setprio 1
	s_waitcnt lgkmcnt(0)
	v_mfma_f32_16x16x32_bf16 v[124:127], v[128:131], v[160:163], 0
	v_mfma_f32_16x16x32_bf16 v[120:123], v[136:139], v[160:163], 0
	v_mfma_f32_16x16x32_bf16 v[112:115], v[128:131], v[184:187], 0
	v_mfma_f32_16x16x32_bf16 v[104:107], v[136:139], v[184:187], 0
	v_mfma_f32_16x16x32_bf16 v[96:99], v[128:131], v[206:209], 0
	v_mfma_f32_16x16x32_bf16 v[88:91], v[136:139], v[206:209], 0
	v_mfma_f32_16x16x32_bf16 v[80:83], v[128:131], v[214:217], 0
	v_mfma_f32_16x16x32_bf16 v[72:75], v[136:139], v[214:217], 0
	v_mfma_f32_16x16x32_bf16 v[124:127], v[132:135], v[180:183], v[124:127]
	v_mfma_f32_16x16x32_bf16 v[120:123], v[140:143], v[180:183], v[120:123]
	v_mfma_f32_16x16x32_bf16 v[112:115], v[132:135], v[192:195], v[112:115]
	v_mfma_f32_16x16x32_bf16 v[104:107], v[140:143], v[192:195], v[104:107]
	v_mfma_f32_16x16x32_bf16 v[96:99], v[132:135], v[210:213], v[96:99]
	v_mfma_f32_16x16x32_bf16 v[88:91], v[140:143], v[210:213], v[88:91]
	v_mfma_f32_16x16x32_bf16 v[80:83], v[132:135], v[218:221], v[80:83]
	v_mfma_f32_16x16x32_bf16 v[72:75], v[140:143], v[218:221], v[72:75]
	s_setprio 0
	s_setprio 1
	v_mfma_f32_16x16x32_bf16 v[116:119], v[144:147], v[160:163], 0
	v_mfma_f32_16x16x32_bf16 v[108:111], v[152:155], v[160:163], 0
	v_mfma_f32_16x16x32_bf16 v[100:103], v[144:147], v[184:187], 0
	v_mfma_f32_16x16x32_bf16 v[92:95], v[152:155], v[184:187], 0
	v_mfma_f32_16x16x32_bf16 v[84:87], v[144:147], v[206:209], 0
	v_mfma_f32_16x16x32_bf16 v[76:79], v[152:155], v[206:209], 0
	v_mfma_f32_16x16x32_bf16 v[68:71], v[144:147], v[214:217], 0
	v_mfma_f32_16x16x32_bf16 v[64:67], v[152:155], v[214:217], 0
	v_mfma_f32_16x16x32_bf16 v[116:119], v[148:151], v[180:183], v[116:119]
	v_mfma_f32_16x16x32_bf16 v[108:111], v[156:159], v[180:183], v[108:111]
	v_mfma_f32_16x16x32_bf16 v[100:103], v[148:151], v[192:195], v[100:103]
	v_mfma_f32_16x16x32_bf16 v[92:95], v[156:159], v[192:195], v[92:95]
	v_mfma_f32_16x16x32_bf16 v[84:87], v[148:151], v[210:213], v[84:87]
	v_mfma_f32_16x16x32_bf16 v[76:79], v[156:159], v[210:213], v[76:79]
	v_mfma_f32_16x16x32_bf16 v[68:71], v[148:151], v[218:221], v[68:71]
	v_mfma_f32_16x16x32_bf16 v[64:67], v[156:159], v[218:221], v[64:67]
	s_setprio 0
	s_barrier
	ds_read_b128 v[160:163], v191 offset:16384
	ds_read_b128 v[180:183], v191 offset:17408
	ds_read_b128 v[184:187], v191 offset:18432
	ds_read_b128 v[192:195], v191 offset:19456
	ds_read_b128 v[206:209], v191 offset:20480
	ds_read_b128 v[210:213], v191 offset:21504
	ds_read_b128 v[214:217], v191 offset:22528
	ds_read_b128 v[218:221], v191 offset:23552
	s_add_i32 s60, s60, s41
	s_mov_b32 m0, s60
	s_add_i32 s57, s57, s41
	global_load_lds_dwordx4 v168, s[58:59]
	s_add_i32 m0, s60, 0x2000
	s_nop 0
	global_load_lds_dwordx4 v174, s[58:59]
	s_add_u32 s58, s58, s16
	s_addc_u32 s59, s59, 0
	s_mov_b32 m0, s57
	s_nop 0
	global_load_lds_dwordx4 v168, s[58:59]
	s_add_i32 m0, s57, 0x2000
	s_nop 0
	global_load_lds_dwordx4 v174, s[58:59]
	s_mov_b32 m0, s42
	s_nop 0
	global_load_lds_dwordx4 v168, s[34:35]
	s_mov_b32 m0, s43
	s_nop 0
	global_load_lds_dwordx4 v174, s[34:35]
	s_waitcnt vmcnt(8)
	s_waitcnt lgkmcnt(0)
	s_barrier
	s_setprio 1
	s_waitcnt lgkmcnt(0)
	v_mfma_f32_16x16x32_bf16 v[60:63], v[128:131], v[160:163], 0
	v_mfma_f32_16x16x32_bf16 v[56:59], v[136:139], v[160:163], 0
	v_mfma_f32_16x16x32_bf16 v[48:51], v[128:131], v[184:187], 0
	v_mfma_f32_16x16x32_bf16 v[40:43], v[136:139], v[184:187], 0
	v_mfma_f32_16x16x32_bf16 v[32:35], v[128:131], v[206:209], 0
	v_mfma_f32_16x16x32_bf16 v[24:27], v[136:139], v[206:209], 0
	v_mfma_f32_16x16x32_bf16 v[16:19], v[128:131], v[214:217], 0
	v_mfma_f32_16x16x32_bf16 v[8:11], v[136:139], v[214:217], 0
	v_mfma_f32_16x16x32_bf16 v[60:63], v[132:135], v[180:183], v[60:63]
	v_mfma_f32_16x16x32_bf16 v[56:59], v[140:143], v[180:183], v[56:59]
	v_mfma_f32_16x16x32_bf16 v[48:51], v[132:135], v[192:195], v[48:51]
	v_mfma_f32_16x16x32_bf16 v[40:43], v[140:143], v[192:195], v[40:43]
	v_mfma_f32_16x16x32_bf16 v[32:35], v[132:135], v[210:213], v[32:35]
	v_mfma_f32_16x16x32_bf16 v[24:27], v[140:143], v[210:213], v[24:27]
	v_mfma_f32_16x16x32_bf16 v[16:19], v[132:135], v[218:221], v[16:19]
	v_mfma_f32_16x16x32_bf16 v[8:11], v[140:143], v[218:221], v[8:11]
	s_setprio 0
	s_setprio 1
	v_mfma_f32_16x16x32_bf16 v[52:55], v[144:147], v[160:163], 0
	v_mfma_f32_16x16x32_bf16 v[44:47], v[152:155], v[160:163], 0
	v_mfma_f32_16x16x32_bf16 v[36:39], v[144:147], v[184:187], 0
	v_mfma_f32_16x16x32_bf16 v[28:31], v[152:155], v[184:187], 0
	v_mfma_f32_16x16x32_bf16 v[20:23], v[144:147], v[206:209], 0
	v_mfma_f32_16x16x32_bf16 v[12:15], v[152:155], v[206:209], 0
	v_mfma_f32_16x16x32_bf16 v[4:7], v[144:147], v[214:217], 0
	v_mfma_f32_16x16x32_bf16 v[0:3], v[152:155], v[214:217], 0
	v_mfma_f32_16x16x32_bf16 v[52:55], v[148:151], v[180:183], v[52:55]
	v_mfma_f32_16x16x32_bf16 v[44:47], v[156:159], v[180:183], v[44:47]
	v_mfma_f32_16x16x32_bf16 v[36:39], v[148:151], v[192:195], v[36:39]
	v_mfma_f32_16x16x32_bf16 v[28:31], v[156:159], v[192:195], v[28:31]
	v_mfma_f32_16x16x32_bf16 v[20:23], v[148:151], v[210:213], v[20:23]
	v_mfma_f32_16x16x32_bf16 v[12:15], v[156:159], v[210:213], v[12:15]
	v_mfma_f32_16x16x32_bf16 v[4:7], v[148:151], v[218:221], v[4:7]
	v_mfma_f32_16x16x32_bf16 v[0:3], v[156:159], v[218:221], v[0:3]
	s_setprio 0
	s_barrier
; #define PG8_STAGE(bufoff, gbase, voff) do { _Pragma("unroll") for (int _i = 0; _i < 2; ++_i) \
;         __builtin_amdgcn_global_load_lds((const unsigned*)((const char*)(gbase) + (voff)[_i]), (LAS unsigned*)(lds + (bufoff) + ldsw + _i * 8192), 16, 0, 0); } while (0)
; #define PG8_LDA(dst, b, h) do { _Pragma("unroll") for (int m = 0; m < 4; ++m) _Pragma("unroll") for (int k = 0; k < 2; ++k) dst[m][k] = *(const LAS bf16x8*)(lds + PG8_SA(b, h) + aoff + m * 2048 + k * 1024); } while (0)
; #define PG8_LDB(dst, b, h) do { _Pragma("unroll") for (int n = 0; n < 2; ++n) _Pragma("unroll") for (int k = 0; k < 2; ++k) dst[n][k] = *(const LAS bf16x8*)(lds + PG8_SB(b, h) + boff + n * 2048 + k * 1024); } while (0)
; #define PG8_MMA(ai, bj, At, Bt) do { __builtin_amdgcn_s_setprio(1); _Pragma("unroll") for (int m = 0; m < 4; ++m) _Pragma("unroll") for (int n = 0; n < 2; ++n) _Pragma("unroll") for (int k = 0; k < 2; ++k) \
;         acc[ai][bj][m][n] = __builtin_amdgcn_mfma_f32_16x16x32_bf16(Bt[n][k], At[m][k], acc[ai][bj][m][n], 0, 0, 0); __builtin_amdgcn_s_setprio(0); } while (0)
; #define PG8_WAIT_V(n) asm volatile("s_waitcnt vmcnt(" #n ")" ::: "memory")
; #define PG8_WAIT_L(n) asm volatile("s_waitcnt lgkmcnt(" #n ")" ::: "memory")
; #define PG8_BAR __builtin_amdgcn_s_barrier()
; #define PG8_SCHED __builtin_amdgcn_sched_barrier(0)
; template <class Epi>
; __device__ __forceinline__ void gemm_phase(LAS unsigned char* lds, const Gemm g, const StaticOrder& S, const Epi& E) {
;     ...
;             PG8_LDB(B0, 1, 0); PG8_LDB(B1, 1, 1); PG8_SCHED; PG8_LDA(At, 1, 0); PG8_STAGE(PG8_SA(0, 1), a2 + hA, voffA);
;             PG8_WAIT_V(8); PG8_WAIT_L(0); PG8_BAR; PG8_MMA(0, 0, At, B0); PG8_MMA(0, 1, At, B1); PG8_BAR; PG8_SCHED;
;             PG8_LDA(At, 1, 1); PG8_STAGE(PG8_SB(1, 0), b3, voffB); PG8_STAGE(PG8_SB(1, 1), b3 + hB, voffB); PG8_STAGE(PG8_SA(1, 0), a3, voffA);
;             PG8_WAIT_V(8); PG8_WAIT_L(0); PG8_BAR; PG8_MMA(1, 0, At, B0); PG8_MMA(1, 1, At, B1); PG8_BAR; PG8_SCHED;
;         }
	ds_read_b128 v[128:131], v240 offset:32768
	ds_read_b128 v[132:135], v240 offset:33792
	ds_read_b128 v[136:139], v240 offset:34816
	ds_read_b128 v[140:143], v240 offset:35840
	ds_read_b128 v[144:147], v240 offset:49152
	ds_read_b128 v[148:151], v240 offset:50176
	ds_read_b128 v[152:155], v240 offset:51200
	ds_read_b128 v[156:159], v240 offset:52224
	ds_read_b128 v[160:163], v191 offset:32768
	ds_read_b128 v[180:183], v191 offset:33792
	ds_read_b128 v[184:187], v191 offset:34816
	ds_read_b128 v[192:195], v191 offset:35840
	ds_read_b128 v[206:209], v191 offset:36864
	ds_read_b128 v[210:213], v191 offset:37888
	ds_read_b128 v[214:217], v191 offset:38912
	ds_read_b128 v[218:221], v191 offset:39936
	s_add_u32 s34, s34, s16
	s_addc_u32 s35, s35, 0
	s_mov_b32 m0, s44
	s_add_i32 s60, 0, 0x18000
	global_load_lds_dwordx4 v168, s[34:35]
	s_mov_b32 m0, s45
	s_nop 0
	global_load_lds_dwordx4 v174, s[34:35]
	s_waitcnt vmcnt(8)
	s_waitcnt lgkmcnt(0)
	s_barrier
	s_setprio 1
	s_waitcnt lgkmcnt(0)
	v_mfma_f32_16x16x32_bf16 v[124:127], v[128:131], v[160:163], v[124:127]
	v_mfma_f32_16x16x32_bf16 v[120:123], v[136:139], v[160:163], v[120:123]
	v_mfma_f32_16x16x32_bf16 v[112:115], v[128:131], v[184:187], v[112:115]
	v_mfma_f32_16x16x32_bf16 v[104:107], v[136:139], v[184:187], v[104:107]
	v_mfma_f32_16x16x32_bf16 v[96:99], v[128:131], v[206:209], v[96:99]
	v_mfma_f32_16x16x32_bf16 v[88:91], v[136:139], v[206:209], v[88:91]
	v_mfma_f32_16x16x32_bf16 v[80:83], v[128:131], v[214:217], v[80:83]
	v_mfma_f32_16x16x32_bf16 v[72:75], v[136:139], v[214:217], v[72:75]
	v_mfma_f32_16x16x32_bf16 v[124:127], v[132:135], v[180:183], v[124:127]
	v_mfma_f32_16x16x32_bf16 v[120:123], v[140:143], v[180:183], v[120:123]
	v_mfma_f32_16x16x32_bf16 v[112:115], v[132:135], v[192:195], v[112:115]
	v_mfma_f32_16x16x32_bf16 v[104:107], v[140:143], v[192:195], v[104:107]
	v_mfma_f32_16x16x32_bf16 v[96:99], v[132:135], v[210:213], v[96:99]
	v_mfma_f32_16x16x32_bf16 v[88:91], v[140:143], v[210:213], v[88:91]
	v_mfma_f32_16x16x32_bf16 v[80:83], v[132:135], v[218:221], v[80:83]
	v_mfma_f32_16x16x32_bf16 v[72:75], v[140:143], v[218:221], v[72:75]
	s_setprio 0
	s_setprio 1
	v_mfma_f32_16x16x32_bf16 v[116:119], v[144:147], v[160:163], v[116:119]
	v_mfma_f32_16x16x32_bf16 v[108:111], v[152:155], v[160:163], v[108:111]
	v_mfma_f32_16x16x32_bf16 v[100:103], v[144:147], v[184:187], v[100:103]
	v_mfma_f32_16x16x32_bf16 v[92:95], v[152:155], v[184:187], v[92:95]
	v_mfma_f32_16x16x32_bf16 v[84:87], v[144:147], v[206:209], v[84:87]
	v_mfma_f32_16x16x32_bf16 v[76:79], v[152:155], v[206:209], v[76:79]
	v_mfma_f32_16x16x32_bf16 v[68:71], v[144:147], v[214:217], v[68:71]
	v_mfma_f32_16x16x32_bf16 v[64:67], v[152:155], v[214:217], v[64:67]
	v_mfma_f32_16x16x32_bf16 v[116:119], v[148:151], v[180:183], v[116:119]
	v_mfma_f32_16x16x32_bf16 v[108:111], v[156:159], v[180:183], v[108:111]
	v_mfma_f32_16x16x32_bf16 v[100:103], v[148:151], v[192:195], v[100:103]
	v_mfma_f32_16x16x32_bf16 v[92:95], v[156:159], v[192:195], v[92:95]
	v_mfma_f32_16x16x32_bf16 v[84:87], v[148:151], v[210:213], v[84:87]
	v_mfma_f32_16x16x32_bf16 v[76:79], v[156:159], v[210:213], v[76:79]
	v_mfma_f32_16x16x32_bf16 v[68:71], v[148:151], v[218:221], v[68:71]
	v_mfma_f32_16x16x32_bf16 v[64:67], v[156:159], v[218:221], v[64:67]
	s_setprio 0
	s_barrier
	ds_read_b128 v[160:163], v191 offset:49152
	ds_read_b128 v[180:183], v191 offset:50176
	ds_read_b128 v[184:187], v191 offset:51200
	ds_read_b128 v[192:195], v191 offset:52224
	ds_read_b128 v[206:209], v191 offset:53248
	ds_read_b128 v[210:213], v191 offset:54272
	ds_read_b128 v[214:217], v191 offset:55296
	ds_read_b128 v[218:221], v191 offset:56320
	s_add_i32 s60, s60, s41
	s_add_i32 m0, s60, 0x4000
	s_nop 0
	global_load_lds_dwordx4 v241, s[58:59]
	s_add_i32 m0, s60, 0x6000
	s_nop 0
	global_load_lds_dwordx4 v242, s[58:59]
	s_sub_u32 s58, s58, s16
	s_subb_u32 s59, s59, 0
	s_mov_b32 m0, s60
	s_nop 0
	global_load_lds_dwordx4 v241, s[58:59]
	s_add_i32 m0, s60, 0x2000
	s_nop 0
	global_load_lds_dwordx4 v242, s[58:59]
	s_sub_u32 s34, s34, s16
	s_subb_u32 s35, s35, 0
	s_mov_b32 m0, s48
	s_nop 0
	global_load_lds_dwordx4 v241, s[34:35]
	s_mov_b32 m0, s49
	s_nop 0
	global_load_lds_dwordx4 v242, s[34:35]
	s_waitcnt vmcnt(8)
	s_waitcnt lgkmcnt(0)
	s_barrier
	s_setprio 1
	s_waitcnt lgkmcnt(0)
	v_mfma_f32_16x16x32_bf16 v[60:63], v[128:131], v[160:163], v[60:63]
	v_mfma_f32_16x16x32_bf16 v[56:59], v[136:139], v[160:163], v[56:59]
	v_mfma_f32_16x16x32_bf16 v[48:51], v[128:131], v[184:187], v[48:51]
	v_mfma_f32_16x16x32_bf16 v[40:43], v[136:139], v[184:187], v[40:43]
	v_mfma_f32_16x16x32_bf16 v[32:35], v[128:131], v[206:209], v[32:35]
	v_mfma_f32_16x16x32_bf16 v[24:27], v[136:139], v[206:209], v[24:27]
	v_mfma_f32_16x16x32_bf16 v[16:19], v[128:131], v[214:217], v[16:19]
	v_mfma_f32_16x16x32_bf16 v[8:11], v[136:139], v[214:217], v[8:11]
	v_mfma_f32_16x16x32_bf16 v[60:63], v[132:135], v[180:183], v[60:63]
	v_mfma_f32_16x16x32_bf16 v[56:59], v[140:143], v[180:183], v[56:59]
	v_mfma_f32_16x16x32_bf16 v[48:51], v[132:135], v[192:195], v[48:51]
	v_mfma_f32_16x16x32_bf16 v[40:43], v[140:143], v[192:195], v[40:43]
	v_mfma_f32_16x16x32_bf16 v[32:35], v[132:135], v[210:213], v[32:35]
	v_mfma_f32_16x16x32_bf16 v[24:27], v[140:143], v[210:213], v[24:27]
	v_mfma_f32_16x16x32_bf16 v[16:19], v[132:135], v[218:221], v[16:19]
	v_mfma_f32_16x16x32_bf16 v[8:11], v[140:143], v[218:221], v[8:11]
	s_setprio 0
	s_setprio 1
	v_mfma_f32_16x16x32_bf16 v[52:55], v[144:147], v[160:163], v[52:55]
	v_mfma_f32_16x16x32_bf16 v[44:47], v[152:155], v[160:163], v[44:47]
	v_mfma_f32_16x16x32_bf16 v[36:39], v[144:147], v[184:187], v[36:39]
	v_mfma_f32_16x16x32_bf16 v[28:31], v[152:155], v[184:187], v[28:31]
	v_mfma_f32_16x16x32_bf16 v[20:23], v[144:147], v[206:209], v[20:23]
	v_mfma_f32_16x16x32_bf16 v[12:15], v[152:155], v[206:209], v[12:15]
	v_mfma_f32_16x16x32_bf16 v[4:7], v[144:147], v[214:217], v[4:7]
	v_mfma_f32_16x16x32_bf16 v[0:3], v[152:155], v[214:217], v[0:3]
	v_mfma_f32_16x16x32_bf16 v[52:55], v[148:151], v[180:183], v[52:55]
	v_mfma_f32_16x16x32_bf16 v[44:47], v[156:159], v[180:183], v[44:47]
	v_mfma_f32_16x16x32_bf16 v[36:39], v[148:151], v[192:195], v[36:39]
	v_mfma_f32_16x16x32_bf16 v[28:31], v[156:159], v[192:195], v[28:31]
	v_mfma_f32_16x16x32_bf16 v[20:23], v[148:151], v[210:213], v[20:23]
	v_mfma_f32_16x16x32_bf16 v[12:15], v[156:159], v[210:213], v[12:15]
	v_mfma_f32_16x16x32_bf16 v[4:7], v[148:151], v[218:221], v[4:7]
	v_mfma_f32_16x16x32_bf16 v[0:3], v[156:159], v[218:221], v[0:3]
	s_setprio 0
	s_barrier
	s_add_u32 s4, s4, 0x100
	s_addc_u32 s5, s5, 0
	s_add_u32 s36, s36, 0x100
	s_addc_u32 s37, s37, 0
	s_cmp_ge_u32 s56, s47
	s_mov_b32 s34, s56
	s_cbranch_scc1 .Lafter_342
	.p2align	6

; #define PG8_STAGE(bufoff, gbase, voff) do { _Pragma("unroll") for (int _i = 0; _i < 2; ++_i) \
;         __builtin_amdgcn_global_load_lds((const unsigned*)((const char*)(gbase) + (voff)[_i]), (LAS unsigned*)(lds + (bufoff) + ldsw + _i * 8192), 16, 0, 0); } while (0)
; #define PG8_LDA(dst, b, h) do { _Pragma("unroll") for (int m = 0; m < 4; ++m) _Pragma("unroll") for (int k = 0; k < 2; ++k) dst[m][k] = *(const LAS bf16x8*)(lds + PG8_SA(b, h) + aoff + m * 2048 + k * 1024); } while (0)
; #define PG8_LDB(dst, b, h) do { _Pragma("unroll") for (int n = 0; n < 2; ++n) _Pragma("unroll") for (int k = 0; k < 2; ++k) dst[n][k] = *(const LAS bf16x8*)(lds + PG8_SB(b, h) + boff + n * 2048 + k * 1024); } while (0)
; #define PG8_MMA(ai, bj, At, Bt) do { __builtin_amdgcn_s_setprio(1); _Pragma("unroll") for (int m = 0; m < 4; ++m) _Pragma("unroll") for (int n = 0; n < 2; ++n) _Pragma("unroll") for (int k = 0; k < 2; ++k) \
;         acc[ai][bj][m][n] = __builtin_amdgcn_mfma_f32_16x16x32_bf16(Bt[n][k], At[m][k], acc[ai][bj][m][n], 0, 0, 0); __builtin_amdgcn_s_setprio(0); } while (0)
; #define PG8_WAIT_V(n) asm volatile("s_waitcnt vmcnt(" #n ")" ::: "memory")
; #define PG8_WAIT_L(n) asm volatile("s_waitcnt lgkmcnt(" #n ")" ::: "memory")
; #define PG8_BAR __builtin_amdgcn_s_barrier()
; #define PG8_SCHED __builtin_amdgcn_sched_barrier(0)
; template <class Epi>
; __device__ __forceinline__ void gemm_phase(LAS unsigned char* lds, const Gemm g, const StaticOrder& S, const Epi& E) {
;     ...
;         for (int t = 0; t < nt; t += 2) {
;             const bool last = (t == nt - 2);
;             const char* a1 = cA + (size_t)(t + 1) * kstep;
;             const char* a2 = last ? nA : cA + (size_t)(t + 2) * kstep; const char* b2 = last ? nB : cB + (size_t)(t + 2) * kstep;
;             const char* a3 = a2 + kstep; const char* b3 = b2 + kstep;
;             PG8_LDB(B0, 0, 0); PG8_LDB(B1, 0, 1); PG8_SCHED; PG8_LDA(At, 0, 0); PG8_STAGE(PG8_SA(1, 1), a1 + hA, voffA);
;             PG8_WAIT_V(8); PG8_WAIT_L(0); PG8_BAR; PG8_MMA(0, 0, At, B0); PG8_MMA(0, 1, At, B1); PG8_BAR; PG8_SCHED;
;             PG8_LDA(At, 0, 1); PG8_STAGE(PG8_SB(0, 0), b2, voffB); PG8_STAGE(PG8_SB(0, 1), b2 + hB, voffB); PG8_STAGE(PG8_SA(0, 0), a2, voffA);
;             PG8_WAIT_V(8); PG8_WAIT_L(0); PG8_BAR; PG8_MMA(1, 0, At, B0); PG8_MMA(1, 1, At, B1); PG8_BAR; PG8_SCHED;
.Lpeel_431:
	s_add_i32 m0, s49, 0xc000
	ds_read_b128 v[128:131], v240
	ds_read_b128 v[132:135], v240 offset:1024
	ds_read_b128 v[136:139], v240 offset:2048
	ds_read_b128 v[140:143], v240 offset:3072
	ds_read_b128 v[144:147], v240 offset:16384
	ds_read_b128 v[148:151], v240 offset:17408
	ds_read_b128 v[152:155], v240 offset:18432
	ds_read_b128 v[156:159], v240 offset:19456
	ds_read_b128 v[180:183], v209
	ds_read_b128 v[184:187], v209 offset:1024
	ds_read_b128 v[188:191], v209 offset:2048
	ds_read_b128 v[192:195], v209 offset:3072
	ds_read_b128 v[210:213], v209 offset:4096
	ds_read_b128 v[214:217], v209 offset:5120
	ds_read_b128 v[218:221], v209 offset:6144
	ds_read_b128 v[222:225], v209 offset:7168
	global_load_lds_dwordx4 v176, s[0:1]
	s_add_i32 m0, s49, 0xe000
	s_nop 0
	global_load_lds_dwordx4 v178, s[0:1]
	s_add_i32 s40, s37, 2
	s_add_u32 s38, s0, 0xfff80080
	s_addc_u32 s39, s1, -1
	s_add_i32 s41, 0, 0x10000
	s_cmp_eq_u32 s57, s37
	s_cselect_b32 s39, s31, s39
	s_cselect_b32 s38, s30, s38
	s_cselect_b32 s69, s35, s33
	s_cselect_b32 s68, s34, s29
	s_add_i32 s37, 0, 0x14000
	s_waitcnt vmcnt(8)
	s_waitcnt lgkmcnt(0)
	s_barrier
	s_setprio 1
	s_waitcnt lgkmcnt(0)
	v_mfma_f32_16x16x32_bf16 v[124:127], v[128:131], v[180:183], 0
	v_mfma_f32_16x16x32_bf16 v[120:123], v[136:139], v[180:183], 0
	v_mfma_f32_16x16x32_bf16 v[108:111], v[128:131], v[188:191], 0
	v_mfma_f32_16x16x32_bf16 v[104:107], v[136:139], v[188:191], 0
	v_mfma_f32_16x16x32_bf16 v[92:95], v[128:131], v[210:213], 0
	v_mfma_f32_16x16x32_bf16 v[88:91], v[136:139], v[210:213], 0
	v_mfma_f32_16x16x32_bf16 v[76:79], v[128:131], v[218:221], 0
	v_mfma_f32_16x16x32_bf16 v[72:75], v[136:139], v[218:221], 0
	v_mfma_f32_16x16x32_bf16 v[124:127], v[132:135], v[184:187], v[124:127]
	v_mfma_f32_16x16x32_bf16 v[120:123], v[140:143], v[184:187], v[120:123]
	v_mfma_f32_16x16x32_bf16 v[108:111], v[132:135], v[192:195], v[108:111]
	v_mfma_f32_16x16x32_bf16 v[104:107], v[140:143], v[192:195], v[104:107]
	v_mfma_f32_16x16x32_bf16 v[92:95], v[132:135], v[214:217], v[92:95]
	v_mfma_f32_16x16x32_bf16 v[88:91], v[140:143], v[214:217], v[88:91]
	v_mfma_f32_16x16x32_bf16 v[76:79], v[132:135], v[222:225], v[76:79]
	v_mfma_f32_16x16x32_bf16 v[72:75], v[140:143], v[222:225], v[72:75]
	s_setprio 0
	s_setprio 1
	v_mfma_f32_16x16x32_bf16 v[116:119], v[144:147], v[180:183], 0
	v_mfma_f32_16x16x32_bf16 v[112:115], v[152:155], v[180:183], 0
	v_mfma_f32_16x16x32_bf16 v[100:103], v[144:147], v[188:191], 0
	v_mfma_f32_16x16x32_bf16 v[96:99], v[152:155], v[188:191], 0
	v_mfma_f32_16x16x32_bf16 v[84:87], v[144:147], v[210:213], 0
	v_mfma_f32_16x16x32_bf16 v[80:83], v[152:155], v[210:213], 0
	v_mfma_f32_16x16x32_bf16 v[68:71], v[144:147], v[218:221], 0
	v_mfma_f32_16x16x32_bf16 v[64:67], v[152:155], v[218:221], 0
	v_mfma_f32_16x16x32_bf16 v[116:119], v[148:151], v[184:187], v[116:119]
	v_mfma_f32_16x16x32_bf16 v[112:115], v[156:159], v[184:187], v[112:115]
	v_mfma_f32_16x16x32_bf16 v[100:103], v[148:151], v[192:195], v[100:103]
	v_mfma_f32_16x16x32_bf16 v[96:99], v[156:159], v[192:195], v[96:99]
	v_mfma_f32_16x16x32_bf16 v[84:87], v[148:151], v[214:217], v[84:87]
	v_mfma_f32_16x16x32_bf16 v[80:83], v[156:159], v[214:217], v[80:83]
	v_mfma_f32_16x16x32_bf16 v[68:71], v[148:151], v[222:225], v[68:71]
	v_mfma_f32_16x16x32_bf16 v[64:67], v[156:159], v[222:225], v[64:67]
	s_setprio 0
	s_barrier
	ds_read_b128 v[180:183], v209 offset:16384
	ds_read_b128 v[184:187], v209 offset:17408
	ds_read_b128 v[188:191], v209 offset:18432
	ds_read_b128 v[192:195], v209 offset:19456
	ds_read_b128 v[210:213], v209 offset:20480
	ds_read_b128 v[214:217], v209 offset:21504
	ds_read_b128 v[218:221], v209 offset:22528
	ds_read_b128 v[222:225], v209 offset:23552
	s_add_i32 s41, s41, s48
	s_mov_b32 m0, s41
	s_add_i32 s37, s37, s48
	global_load_lds_dwordx4 v168, s[68:69]
	s_add_i32 m0, s41, 0x2000
	s_nop 0
	global_load_lds_dwordx4 v164, s[68:69]
	s_add_u32 s68, s68, s46
	s_addc_u32 s69, s69, 0
	s_mov_b32 m0, s37
	s_nop 0
	global_load_lds_dwordx4 v168, s[68:69]
	s_add_i32 m0, s37, 0x2000
	s_nop 0
	global_load_lds_dwordx4 v164, s[68:69]
	s_mov_b32 m0, s49
	s_nop 0
	global_load_lds_dwordx4 v160, s[38:39]
	s_mov_b32 m0, s50
	s_nop 0
	global_load_lds_dwordx4 v162, s[38:39]
	s_waitcnt vmcnt(8)
	s_waitcnt lgkmcnt(0)
	s_barrier
	s_setprio 1
	s_waitcnt lgkmcnt(0)
	v_mfma_f32_16x16x32_bf16 v[60:63], v[128:131], v[180:183], 0
	v_mfma_f32_16x16x32_bf16 v[56:59], v[136:139], v[180:183], 0
	v_mfma_f32_16x16x32_bf16 v[44:47], v[128:131], v[188:191], 0
	v_mfma_f32_16x16x32_bf16 v[40:43], v[136:139], v[188:191], 0
	v_mfma_f32_16x16x32_bf16 v[28:31], v[128:131], v[210:213], 0
	v_mfma_f32_16x16x32_bf16 v[24:27], v[136:139], v[210:213], 0
	v_mfma_f32_16x16x32_bf16 v[12:15], v[128:131], v[218:221], 0
	v_mfma_f32_16x16x32_bf16 v[8:11], v[136:139], v[218:221], 0
	v_mfma_f32_16x16x32_bf16 v[60:63], v[132:135], v[184:187], v[60:63]
	v_mfma_f32_16x16x32_bf16 v[56:59], v[140:143], v[184:187], v[56:59]
	v_mfma_f32_16x16x32_bf16 v[44:47], v[132:135], v[192:195], v[44:47]
	v_mfma_f32_16x16x32_bf16 v[40:43], v[140:143], v[192:195], v[40:43]
	v_mfma_f32_16x16x32_bf16 v[28:31], v[132:135], v[214:217], v[28:31]
	v_mfma_f32_16x16x32_bf16 v[24:27], v[140:143], v[214:217], v[24:27]
	v_mfma_f32_16x16x32_bf16 v[12:15], v[132:135], v[222:225], v[12:15]
	v_mfma_f32_16x16x32_bf16 v[8:11], v[140:143], v[222:225], v[8:11]
	s_setprio 0
	s_setprio 1
	v_mfma_f32_16x16x32_bf16 v[52:55], v[144:147], v[180:183], 0
	v_mfma_f32_16x16x32_bf16 v[48:51], v[152:155], v[180:183], 0
	v_mfma_f32_16x16x32_bf16 v[36:39], v[144:147], v[188:191], 0
	v_mfma_f32_16x16x32_bf16 v[32:35], v[152:155], v[188:191], 0
	v_mfma_f32_16x16x32_bf16 v[20:23], v[144:147], v[210:213], 0
	v_mfma_f32_16x16x32_bf16 v[16:19], v[152:155], v[210:213], 0
	v_mfma_f32_16x16x32_bf16 v[4:7], v[144:147], v[218:221], 0
	v_mfma_f32_16x16x32_bf16 v[0:3], v[152:155], v[218:221], 0
	v_mfma_f32_16x16x32_bf16 v[52:55], v[148:151], v[184:187], v[52:55]
	v_mfma_f32_16x16x32_bf16 v[48:51], v[156:159], v[184:187], v[48:51]
	v_mfma_f32_16x16x32_bf16 v[36:39], v[148:151], v[192:195], v[36:39]
	v_mfma_f32_16x16x32_bf16 v[32:35], v[156:159], v[192:195], v[32:35]
	v_mfma_f32_16x16x32_bf16 v[20:23], v[148:151], v[214:217], v[20:23]
	v_mfma_f32_16x16x32_bf16 v[16:19], v[156:159], v[214:217], v[16:19]
	v_mfma_f32_16x16x32_bf16 v[4:7], v[148:151], v[222:225], v[4:7]
	v_mfma_f32_16x16x32_bf16 v[0:3], v[156:159], v[222:225], v[0:3]
	s_setprio 0
	s_barrier
; #define PG8_STAGE(bufoff, gbase, voff) do { _Pragma("unroll") for (int _i = 0; _i < 2; ++_i) \
;         __builtin_amdgcn_global_load_lds((const unsigned*)((const char*)(gbase) + (voff)[_i]), (LAS unsigned*)(lds + (bufoff) + ldsw + _i * 8192), 16, 0, 0); } while (0)
; #define PG8_LDA(dst, b, h) do { _Pragma("unroll") for (int m = 0; m < 4; ++m) _Pragma("unroll") for (int k = 0; k < 2; ++k) dst[m][k] = *(const LAS bf16x8*)(lds + PG8_SA(b, h) + aoff + m * 2048 + k * 1024); } while (0)
; #define PG8_LDB(dst, b, h) do { _Pragma("unroll") for (int n = 0; n < 2; ++n) _Pragma("unroll") for (int k = 0; k < 2; ++k) dst[n][k] = *(const LAS bf16x8*)(lds + PG8_SB(b, h) + boff + n * 2048 + k * 1024); } while (0)
; #define PG8_WAIT_V(n) asm volatile("s_waitcnt vmcnt(" #n ")" ::: "memory")
; #define PG8_WAIT_L(n) asm volatile("s_waitcnt lgkmcnt(" #n ")" ::: "memory")
; template <class Epi>
; __device__ __forceinline__ void gemm_phase(LAS unsigned char* lds, const Gemm g, const StaticOrder& S, const Epi& E) {
;     ...
;         for (int t = 0; t < nt; t += 2) {
;             const bool last = (t == nt - 2);
;             const char* a1 = cA + (size_t)(t + 1) * kstep;
;             const char* a2 = last ? nA : cA + (size_t)(t + 2) * kstep; const char* b2 = last ? nB : cB + (size_t)(t + 2) * kstep;
;             const char* a3 = a2 + kstep; const char* b3 = b2 + kstep;
;             PG8_LDB(B0, 0, 0); PG8_LDB(B1, 0, 1); PG8_SCHED; PG8_LDA(At, 0, 0); PG8_STAGE(PG8_SA(1, 1), a1 + hA, voffA);
;             PG8_WAIT_V(8); PG8_WAIT_L(0); PG8_BAR; PG8_MMA(0, 0, At, B0); PG8_MMA(0, 1, At, B1); PG8_BAR; PG8_SCHED;
;             PG8_LDA(At, 0, 1); PG8_STAGE(PG8_SB(0, 0), b2, voffB); PG8_STAGE(PG8_SB(0, 1), b2 + hB, voffB); PG8_STAGE(PG8_SA(0, 0), a2, voffA);
;             PG8_WAIT_V(8); PG8_WAIT_L(0); PG8_BAR; PG8_MMA(1, 0, At, B0); PG8_MMA(1, 1, At, B1); PG8_BAR; PG8_SCHED;
;             PG8_LDB(B0, 1, 0); PG8_LDB(B1, 1, 1); PG8_SCHED; PG8_LDA(At, 1, 0); PG8_STAGE(PG8_SA(0, 1), a2 + hA, voffA);
;             PG8_WAIT_V(8); PG8_WAIT_L(0); PG8_BAR; PG8_MMA(0, 0, At, B0); PG8_MMA(0, 1, At, B1); PG8_BAR; PG8_SCHED;
;             PG8_LDA(At, 1, 1); PG8_STAGE(PG8_SB(1, 0), b3, voffB); PG8_STAGE(PG8_SB(1, 1), b3 + hB, voffB); PG8_STAGE(PG8_SA(1, 0), a3, voffA);
;             PG8_WAIT_V(8); PG8_WAIT_L(0); PG8_BAR; PG8_MMA(1, 0, At, B0); PG8_MMA(1, 1, At, B1); PG8_BAR; PG8_SCHED;
	ds_read_b128 v[128:131], v240 offset:32768
	ds_read_b128 v[132:135], v240 offset:33792
	ds_read_b128 v[136:139], v240 offset:34816
	ds_read_b128 v[140:143], v240 offset:35840
	ds_read_b128 v[144:147], v240 offset:49152
	ds_read_b128 v[148:151], v240 offset:50176
	ds_read_b128 v[152:155], v240 offset:51200
	ds_read_b128 v[156:159], v240 offset:52224
	ds_read_b128 v[180:183], v209 offset:32768
	ds_read_b128 v[184:187], v209 offset:33792
	ds_read_b128 v[188:191], v209 offset:34816
	ds_read_b128 v[192:195], v209 offset:35840
	ds_read_b128 v[210:213], v209 offset:36864
	ds_read_b128 v[214:217], v209 offset:37888
	ds_read_b128 v[218:221], v209 offset:38912
	ds_read_b128 v[222:225], v209 offset:39936
	s_add_u32 s38, s38, 0x80000
	s_addc_u32 s39, s39, 0
	s_mov_b32 m0, s51
	s_add_i32 s41, 0, 0x18000
	global_load_lds_dwordx4 v160, s[38:39]
	s_mov_b32 m0, s52
	s_nop 0
	global_load_lds_dwordx4 v162, s[38:39]
	s_waitcnt vmcnt(8)
	s_waitcnt lgkmcnt(0)
	s_barrier
	s_setprio 1
	s_waitcnt lgkmcnt(0)
	v_mfma_f32_16x16x32_bf16 v[124:127], v[128:131], v[180:183], v[124:127]
	v_mfma_f32_16x16x32_bf16 v[120:123], v[136:139], v[180:183], v[120:123]
	v_mfma_f32_16x16x32_bf16 v[108:111], v[128:131], v[188:191], v[108:111]
	v_mfma_f32_16x16x32_bf16 v[104:107], v[136:139], v[188:191], v[104:107]
	v_mfma_f32_16x16x32_bf16 v[92:95], v[128:131], v[210:213], v[92:95]
	v_mfma_f32_16x16x32_bf16 v[88:91], v[136:139], v[210:213], v[88:91]
	v_mfma_f32_16x16x32_bf16 v[76:79], v[128:131], v[218:221], v[76:79]
	v_mfma_f32_16x16x32_bf16 v[72:75], v[136:139], v[218:221], v[72:75]
	v_mfma_f32_16x16x32_bf16 v[124:127], v[132:135], v[184:187], v[124:127]
	v_mfma_f32_16x16x32_bf16 v[120:123], v[140:143], v[184:187], v[120:123]
	v_mfma_f32_16x16x32_bf16 v[108:111], v[132:135], v[192:195], v[108:111]
	v_mfma_f32_16x16x32_bf16 v[104:107], v[140:143], v[192:195], v[104:107]
	v_mfma_f32_16x16x32_bf16 v[92:95], v[132:135], v[214:217], v[92:95]
	v_mfma_f32_16x16x32_bf16 v[88:91], v[140:143], v[214:217], v[88:91]
	v_mfma_f32_16x16x32_bf16 v[76:79], v[132:135], v[222:225], v[76:79]
	v_mfma_f32_16x16x32_bf16 v[72:75], v[140:143], v[222:225], v[72:75]
	s_setprio 0
	s_setprio 1
	v_mfma_f32_16x16x32_bf16 v[116:119], v[144:147], v[180:183], v[116:119]
	v_mfma_f32_16x16x32_bf16 v[112:115], v[152:155], v[180:183], v[112:115]
	v_mfma_f32_16x16x32_bf16 v[100:103], v[144:147], v[188:191], v[100:103]
	v_mfma_f32_16x16x32_bf16 v[96:99], v[152:155], v[188:191], v[96:99]
	v_mfma_f32_16x16x32_bf16 v[84:87], v[144:147], v[210:213], v[84:87]
	v_mfma_f32_16x16x32_bf16 v[80:83], v[152:155], v[210:213], v[80:83]
	v_mfma_f32_16x16x32_bf16 v[68:71], v[144:147], v[218:221], v[68:71]
	v_mfma_f32_16x16x32_bf16 v[64:67], v[152:155], v[218:221], v[64:67]
	v_mfma_f32_16x16x32_bf16 v[116:119], v[148:151], v[184:187], v[116:119]
	v_mfma_f32_16x16x32_bf16 v[112:115], v[156:159], v[184:187], v[112:115]
	v_mfma_f32_16x16x32_bf16 v[100:103], v[148:151], v[192:195], v[100:103]
	v_mfma_f32_16x16x32_bf16 v[96:99], v[156:159], v[192:195], v[96:99]
	v_mfma_f32_16x16x32_bf16 v[84:87], v[148:151], v[214:217], v[84:87]
	v_mfma_f32_16x16x32_bf16 v[80:83], v[156:159], v[214:217], v[80:83]
	v_mfma_f32_16x16x32_bf16 v[68:71], v[148:151], v[222:225], v[68:71]
	v_mfma_f32_16x16x32_bf16 v[64:67], v[156:159], v[222:225], v[64:67]
	s_setprio 0
	s_barrier
	ds_read_b128 v[180:183], v209 offset:49152
	ds_read_b128 v[184:187], v209 offset:50176
	ds_read_b128 v[188:191], v209 offset:51200
	ds_read_b128 v[192:195], v209 offset:52224
	ds_read_b128 v[210:213], v209 offset:53248
	ds_read_b128 v[214:217], v209 offset:54272
	ds_read_b128 v[218:221], v209 offset:55296
	ds_read_b128 v[222:225], v209 offset:56320
	s_add_i32 s41, s41, s48
	s_add_i32 m0, s41, 0x4000
	s_nop 0
	global_load_lds_dwordx4 v241, s[68:69]
	s_add_i32 m0, s41, 0x6000
	s_nop 0
	global_load_lds_dwordx4 v242, s[68:69]
	s_sub_u32 s68, s68, s46
	s_subb_u32 s69, s69, 0
	s_mov_b32 m0, s41
	s_nop 0
	global_load_lds_dwordx4 v241, s[68:69]
	s_add_i32 m0, s41, 0x2000
	s_nop 0
	global_load_lds_dwordx4 v242, s[68:69]
	s_sub_u32 s38, s38, 0x80000
	s_subb_u32 s39, s39, 0
	s_mov_b32 m0, s55
	s_nop 0
	global_load_lds_dwordx4 v243, s[38:39]
	s_mov_b32 m0, s56
	s_nop 0
	global_load_lds_dwordx4 v244, s[38:39]
	s_waitcnt vmcnt(8)
	s_waitcnt lgkmcnt(0)
	s_barrier
	s_setprio 1
	s_waitcnt lgkmcnt(0)
	v_mfma_f32_16x16x32_bf16 v[60:63], v[128:131], v[180:183], v[60:63]
	v_mfma_f32_16x16x32_bf16 v[56:59], v[136:139], v[180:183], v[56:59]
	v_mfma_f32_16x16x32_bf16 v[44:47], v[128:131], v[188:191], v[44:47]
	v_mfma_f32_16x16x32_bf16 v[40:43], v[136:139], v[188:191], v[40:43]
	v_mfma_f32_16x16x32_bf16 v[28:31], v[128:131], v[210:213], v[28:31]
	v_mfma_f32_16x16x32_bf16 v[24:27], v[136:139], v[210:213], v[24:27]
	v_mfma_f32_16x16x32_bf16 v[12:15], v[128:131], v[218:221], v[12:15]
	v_mfma_f32_16x16x32_bf16 v[8:11], v[136:139], v[218:221], v[8:11]
	v_mfma_f32_16x16x32_bf16 v[60:63], v[132:135], v[184:187], v[60:63]
	v_mfma_f32_16x16x32_bf16 v[56:59], v[140:143], v[184:187], v[56:59]
	v_mfma_f32_16x16x32_bf16 v[44:47], v[132:135], v[192:195], v[44:47]
	v_mfma_f32_16x16x32_bf16 v[40:43], v[140:143], v[192:195], v[40:43]
	v_mfma_f32_16x16x32_bf16 v[28:31], v[132:135], v[214:217], v[28:31]
	v_mfma_f32_16x16x32_bf16 v[24:27], v[140:143], v[214:217], v[24:27]
	v_mfma_f32_16x16x32_bf16 v[12:15], v[132:135], v[222:225], v[12:15]
	v_mfma_f32_16x16x32_bf16 v[8:11], v[140:143], v[222:225], v[8:11]
	s_setprio 0
	s_setprio 1
	v_mfma_f32_16x16x32_bf16 v[52:55], v[144:147], v[180:183], v[52:55]
	v_mfma_f32_16x16x32_bf16 v[48:51], v[152:155], v[180:183], v[48:51]
	v_mfma_f32_16x16x32_bf16 v[36:39], v[144:147], v[188:191], v[36:39]
	v_mfma_f32_16x16x32_bf16 v[32:35], v[152:155], v[188:191], v[32:35]
	v_mfma_f32_16x16x32_bf16 v[20:23], v[144:147], v[210:213], v[20:23]
	v_mfma_f32_16x16x32_bf16 v[16:19], v[152:155], v[210:213], v[16:19]
	v_mfma_f32_16x16x32_bf16 v[4:7], v[144:147], v[218:221], v[4:7]
	v_mfma_f32_16x16x32_bf16 v[0:3], v[152:155], v[218:221], v[0:3]
	v_mfma_f32_16x16x32_bf16 v[52:55], v[148:151], v[184:187], v[52:55]
	v_mfma_f32_16x16x32_bf16 v[48:51], v[156:159], v[184:187], v[48:51]
	v_mfma_f32_16x16x32_bf16 v[36:39], v[148:151], v[192:195], v[36:39]
	v_mfma_f32_16x16x32_bf16 v[32:35], v[156:159], v[192:195], v[32:35]
	v_mfma_f32_16x16x32_bf16 v[20:23], v[148:151], v[214:217], v[20:23]
	v_mfma_f32_16x16x32_bf16 v[16:19], v[156:159], v[214:217], v[16:19]
	v_mfma_f32_16x16x32_bf16 v[4:7], v[148:151], v[222:225], v[4:7]
	v_mfma_f32_16x16x32_bf16 v[0:3], v[156:159], v[222:225], v[0:3]
	s_setprio 0
	s_barrier
	s_add_u32 s0, s0, 0x100
	s_addc_u32 s1, s1, 0
	s_add_u32 s29, s29, 0x100
	s_addc_u32 s33, s33, 0
	s_cmp_ge_u32 s40, s54
	s_mov_b32 s37, s40
	s_cbranch_scc1 .Lafter_431
	.p2align	6
